# grid barrier: XCD leader skips the L2 write-back after phases whose stores are all write-through (out/down GEMM, post phases)
# speedup vs baseline: 1.0086x; 1.0086x over previous
.Lxb_leader:
	v_readlane_b32 s98, v252, 2
	s_nop 0
	s_sub_i32 s98, s98, 4
	s_cmp_lt_i32 s98, 0
	s_cbranch_scc1 .Lxb_flush
	s_mul_i32 s99, s98, 0x1746
	s_lshr_b32 s99, s99, 16
	s_mul_i32 s99, s99, 11
	s_sub_i32 s98, s98, s99
	s_lshl_b32 s98, 1, s98
	s_and_b32 s98, s98, 0x660
	s_cmp_lg_u32 s98, 0
	s_cbranch_scc1 .Lxb_noflush

.Lxb_noflush:
	s_add_u32 s10, s38, 0x3400
	s_addc_u32 s11, s39, 0
	global_atomic_add v5, v228, s[10:11]
	s_mov_b32 s9, 0
